# grid barrier: XCD leader publishes the per-XCD generation before (not after) its own L1 invalidate
# speedup vs baseline: 1.0187x; 1.0020x over previous
.LBB0_92:
	s_or_b64 exec, exec, s[20:21]
	s_mov_b64 s[20:21], exec
	v_mbcnt_lo_u32_b32 v0, s20, 0
	v_mbcnt_hi_u32_b32 v0, s21, v0
	v_cmp_eq_u32_e32 vcc, 0, v0
	s_waitcnt vmcnt(0)
	s_and_saveexec_b64 s[22:23], vcc
	s_cbranch_execz .LBB0_94
	s_bcnt1_i32_b64 s20, s[20:21]
	v_mov_b32_e32 v0, s20
	v_readlane_b32 s20, v252, 54
	v_readlane_b32 s21, v252, 55
	s_nop 4
	global_atomic_add v179, v0, s[20:21]
.LBB0_94:
	s_or_b64 exec, exec, s[22:23]
	buffer_inv sc1
	s_waitcnt vmcnt(0)
